# remove s_setprio flips in the causal attention phase (P7); bf16 MFMA unchanged
# baseline (speedup 1.0000x reference)
; #define LAS __attribute__((address_space(3)))
; __global__ void __launch_bounds__(NWAVES * 64, 2) mk_fwd(Params P) {
;     extern __shared__ __attribute__((aligned(16))) unsigned char lds_raw[];
;     ...
;     unsigned* ctl = (unsigned*)(WSB + WS_CTL);
;     for (int u = threadIdx.x; u < (LDS_BYTES - LDSCTL_OFF) / 4; u += NWAVES * 64) ((LAS unsigned*)(LDSP + LDSCTL_OFF))[u] = 0u;
;     __syncthreads();
_Z6mk_fwd6Params:
	s_load_dwordx16 s[68:83], s[0:1], 0x0
	s_load_dwordx16 s[36:51], s[0:1], 0x40
	s_load_dwordx16 s[52:67], s[0:1], 0x80
	s_load_dwordx16 s[4:19], s[0:1], 0xc0
	s_load_dwordx2 s[34:35], s[0:1], 0x100
	v_mov_b32_e32 v254, v0
	v_lshl_add_u32 v0, v254, 2, 0
	v_add_u32_e32 v1, 0x21800, v0
	s_waitcnt lgkmcnt(0)
	v_writelane_b32 v255, s4, 0
	v_mov_b32_e32 v2, 0
	s_nop 0
	v_writelane_b32 v255, s5, 1
	v_writelane_b32 v255, s6, 2
	v_writelane_b32 v255, s7, 3
	v_writelane_b32 v255, s8, 4
	v_writelane_b32 v255, s9, 5
	v_writelane_b32 v255, s10, 6
	v_writelane_b32 v255, s11, 7
	v_writelane_b32 v255, s12, 8
	v_writelane_b32 v255, s13, 9
	v_writelane_b32 v255, s14, 10
	v_writelane_b32 v255, s15, 11
	v_writelane_b32 v255, s16, 12
	v_writelane_b32 v255, s17, 13
	v_writelane_b32 v255, s18, 14
	v_writelane_b32 v255, s19, 15
	s_mov_b32 s4, 0
	s_mov_b32 s5, 1
	s_mov_b64 s[6:7], 0
	s_mov_b32 s8, s4
	s_branch .LBB0_2


; #define ATT_SBAR() __builtin_amdgcn_sched_barrier(0)
; #define QP_LD(d, s) do { ka[s] = *reinterpret_cast<const bf16x8*>(r0 + (d) * 32); kb[s] = *reinterpret_cast<const bf16x8*>(r1 + (d) * 32); } while (0)
; #define ATT_TRB(vb, off) __builtin_amdgcn_ds_read_tr16_b64_v4i16((LAS s16x4*)(unsigned)((vb) + (off)))
; #define QP_LD(d, s) do { ka[s] = *reinterpret_cast<const bf16x8*>(r0 + (d) * 32); kb[s] = *reinterpret_cast<const bf16x8*>(r1 + (d) * 32); } while (0)
; template <int DK> __device__ __forceinline__ void qkt_pipe_pv(f32x16& p0, f32x16& p1, const char* Ks, const bf16x8* qr, int r32, int hi, int vb, s16x4 (&F)[8]) {
;     constexpr int ND = DK / 16, KR = DK * 2 + 16;
;     const char* r0 = Ks + ATT_KSWZ(r32, hi * 16, KR); const char* r1 = Ks + ATT_KSWZ(32 + r32, hi * 16, KR);
;     bf16x8 ka[3], kb[3];
;     ...
;     QP_LD(0, 0); QP_LD(1, 1); QP_LD(2, 2); ATT_SBAR();
;     p0 = f32x16{}; p1 = f32x16{};
;     __builtin_amdgcn_s_setprio(1);
; #pragma unroll
;     for (int d0 = 0; d0 < ND; ++d0) {
;         p0 = __builtin_amdgcn_mfma_f32_32x32x16_bf16(ka[d0 % 3], qr[d0], p0, 0, 0, 0);
;         p1 = __builtin_amdgcn_mfma_f32_32x32x16_bf16(kb[d0 % 3], qr[d0], p1, 0, 0, 0);
;         if (d0 + 3 < ND) QP_LD(d0 + 3, d0 % 3);
;         if (d0 == ND - 3) { F[0] = ATT_TRB(vb, v_rd_off(0, 0, 0)); F[1] = ATT_TRB(vb, v_rd_off(0, 0, 1)); F[2] = ATT_TRB(vb, v_rd_off(0, 1, 0)); F[3] = ATT_TRB(vb, v_rd_off(0, 1, 1)); }
;         if (d0 == ND - 2) { F[4] = ATT_TRB(vb, v_rd_off(0, 2, 0)); F[5] = ATT_TRB(vb, v_rd_off(0, 2, 1)); F[6] = ATT_TRB(vb, v_rd_off(0, 3, 0)); F[7] = ATT_TRB(vb, v_rd_off(0, 3, 1)); }
;         ATT_SBAR(); }
;     __builtin_amdgcn_s_setprio(0);
;     ...
; }
; __device__ __forceinline__ void pv_d0_pre(f32x16* o, int vb, bf16x8 pa0, bf16x8 pa1, bf16x8 pa2, bf16x8 pa3, s16x4 (&F)[8]) {
;     s16x4 G[8];
;     ...
;     PVB_RD(1, G); ATT_SBAR(); PVB_MM(0, F); ATT_SBAR();
;     PVB_RD(2, F); ATT_SBAR(); PVB_MM(1, G); ATT_SBAR();
;     PVB_RD(3, G); ATT_SBAR(); PVB_MM(2, F); ATT_SBAR();
;     PVB_MM(3, G);
;     ...
; }
.LBB0_803:
	v_lshlrev_b32_e32 v18, 4, v202
	v_lshlrev_b32_e32 v0, 3, v202
	v_and_b32_e32 v18, 0xc0, v18
	v_lshlrev_b32_e32 v19, 1, v202
	v_and_or_b32 v18, v0, 24, v18
	v_and_b32_e32 v19, 32, v19
	v_and_b32_e32 v0, 0x100, v0
	v_or3_b32 v0, v18, v19, v0
	s_waitcnt lgkmcnt(0)
	s_barrier
	v_add_u32_e32 v198, 0xe400, v195
	ds_read_b128 v[18:21], v195 offset:58368
	ds_read_b128 v[22:25], v195 offset:58400
	ds_read_b128 v[26:29], v198 offset:12800
	ds_read_b128 v[30:33], v195 offset:58432
	ds_read_b128 v[34:37], v198 offset:12832
	ds_read_b128 v[38:41], v198 offset:12864
	s_waitcnt lgkmcnt(5)
	v_mfma_f32_32x32x16_bf16 v[82:97], v[18:21], v[98:101], 0
	ds_read_b128 v[18:21], v195 offset:58464
	ds_read_b128 v[42:45], v198 offset:12896
	s_cmp_lg_u32 0, -1
	s_cselect_b32 s0, 0, 0
	s_waitcnt lgkmcnt(5)
	v_mfma_f32_32x32x16_bf16 v[66:81], v[26:29], v[98:101], 0
	v_mfma_f32_32x32x16_bf16 v[82:97], v[22:25], v[102:105], v[82:97]
	ds_read_b128 v[22:25], v195 offset:58496
	ds_read_b128 v[26:29], v198 offset:12928
	s_waitcnt lgkmcnt(5)
	v_mfma_f32_32x32x16_bf16 v[66:81], v[34:37], v[102:105], v[66:81]
	v_mfma_f32_32x32x16_bf16 v[82:97], v[30:33], v[106:109], v[82:97]
	ds_read_b128 v[30:33], v195 offset:58528
	ds_read_b128 v[34:37], v198 offset:12960
	s_waitcnt lgkmcnt(6)
	v_mfma_f32_32x32x16_bf16 v[66:81], v[38:41], v[106:109], v[66:81]
	s_waitcnt lgkmcnt(5)
	v_mfma_f32_32x32x16_bf16 v[82:97], v[18:21], v[110:113], v[82:97]
	ds_read_b128 v[18:21], v195 offset:58560
	ds_read_b128 v[38:41], v198 offset:12992
	s_waitcnt lgkmcnt(6)
	v_mfma_f32_32x32x16_bf16 v[66:81], v[42:45], v[110:113], v[66:81]
	s_waitcnt lgkmcnt(5)
	v_mfma_f32_32x32x16_bf16 v[82:97], v[22:25], v[114:117], v[82:97]
	ds_read_b128 v[22:25], v195 offset:58592
	ds_read_b128 v[42:45], v198 offset:13024
	s_waitcnt lgkmcnt(6)
	v_mfma_f32_32x32x16_bf16 v[66:81], v[26:29], v[114:117], v[66:81]
	s_waitcnt lgkmcnt(5)
	v_mfma_f32_32x32x16_bf16 v[82:97], v[30:33], v[118:121], v[82:97]
	ds_read_b128 v[26:29], v195 offset:58624
	ds_read_b128 v[30:33], v198 offset:13056
	s_waitcnt lgkmcnt(6)
	v_mfma_f32_32x32x16_bf16 v[66:81], v[34:37], v[118:121], v[66:81]
	s_waitcnt lgkmcnt(5)
	v_mfma_f32_32x32x16_bf16 v[82:97], v[18:21], v[122:125], v[82:97]
	ds_read_b128 v[18:21], v195 offset:58656
	ds_read_b128 v[34:37], v198 offset:13088
	s_waitcnt lgkmcnt(6)
	v_mfma_f32_32x32x16_bf16 v[66:81], v[38:41], v[122:125], v[66:81]
	s_waitcnt lgkmcnt(5)
	v_mfma_f32_32x32x16_bf16 v[82:97], v[22:25], v[126:129], v[82:97]
	ds_read_b128 v[22:25], v195 offset:58688
	ds_read_b128 v[38:41], v198 offset:13120
	s_waitcnt lgkmcnt(6)
	v_mfma_f32_32x32x16_bf16 v[66:81], v[42:45], v[126:129], v[66:81]
	s_waitcnt lgkmcnt(5)
	v_mfma_f32_32x32x16_bf16 v[82:97], v[26:29], v[130:133], v[82:97]
	ds_read_b128 v[26:29], v195 offset:58720
	ds_read_b128 v[42:45], v198 offset:13152
	s_waitcnt lgkmcnt(6)
	v_mfma_f32_32x32x16_bf16 v[66:81], v[30:33], v[130:133], v[66:81]
	s_waitcnt lgkmcnt(5)
	v_mfma_f32_32x32x16_bf16 v[82:97], v[18:21], v[158:161], v[82:97]
	v_add_u32_e32 v197, 0, v0
	v_add_u32_e32 v0, s0, v0
	ds_read_b64_tr_b16 v[46:47], v197
	ds_read_b64_tr_b16 v[48:49], v0 offset:2048
	ds_read_b64_tr_b16 v[50:51], v0 offset:4096
	ds_read_b64_tr_b16 v[52:53], v0 offset:6144
	s_waitcnt lgkmcnt(8)
	v_mfma_f32_32x32x16_bf16 v[66:81], v[34:37], v[158:161], v[66:81]
	s_waitcnt lgkmcnt(7)
	v_mfma_f32_32x32x16_bf16 v[82:97], v[22:25], v[134:137], v[82:97]
	ds_read_b64_tr_b16 v[34:35], v0 offset:8192
	ds_read_b64_tr_b16 v[36:37], v0 offset:10240
	ds_read_b64_tr_b16 v[54:55], v0 offset:12288
	ds_read_b64_tr_b16 v[56:57], v0 offset:14336
	s_waitcnt lgkmcnt(10)
	v_mfma_f32_32x32x16_bf16 v[66:81], v[38:41], v[134:137], v[66:81]
	s_waitcnt lgkmcnt(9)
	v_mfma_f32_32x32x16_bf16 v[82:97], v[26:29], v[162:165], v[82:97]
	s_waitcnt lgkmcnt(8)
	v_mfma_f32_32x32x16_bf16 v[66:81], v[42:45], v[162:165], v[66:81]
	ds_read_b64_tr_b16 v[58:59], v0 offset:512
	ds_read_b64_tr_b16 v[60:61], v0 offset:2560
	ds_read_b64_tr_b16 v[62:63], v0 offset:4608
	ds_read_b64_tr_b16 v[64:65], v0 offset:6656
	ds_read_b64_tr_b16 v[206:207], v0 offset:8704
	ds_read_b64_tr_b16 v[208:209], v0 offset:10752
	ds_read_b64_tr_b16 v[210:211], v0 offset:12800
	ds_read_b64_tr_b16 v[212:213], v0 offset:14848
	s_waitcnt lgkmcnt(14)
	v_mfma_f32_32x32x16_bf16 v[18:33], v[166:169], v[46:49], v[2:17]
	s_waitcnt lgkmcnt(12)
	v_mfma_f32_32x32x16_bf16 v[18:33], v[170:173], v[50:53], v[18:33]
	s_waitcnt lgkmcnt(10)
	v_mfma_f32_32x32x16_bf16 v[18:33], v[174:177], v[34:37], v[18:33]
	s_waitcnt lgkmcnt(8)
	v_mfma_f32_32x32x16_bf16 v[18:33], v[178:181], v[54:57], v[18:33]
	ds_read_b64_tr_b16 v[214:215], v0 offset:1024
	ds_read_b64_tr_b16 v[216:217], v0 offset:3072
	ds_read_b64_tr_b16 v[218:219], v0 offset:5120
	ds_read_b64_tr_b16 v[220:221], v0 offset:7168
	ds_read_b64_tr_b16 v[222:223], v0 offset:9216
	ds_read_b64_tr_b16 v[224:225], v0 offset:11264
	ds_read_b64_tr_b16 v[226:227], v0 offset:13312
	ds_read_b64_tr_b16 v[228:229], v0 offset:15360
	s_waitcnt lgkmcnt(14)
	v_mfma_f32_32x32x16_bf16 v[34:49], v[166:169], v[58:61], v[2:17]
	s_waitcnt lgkmcnt(12)
	v_mfma_f32_32x32x16_bf16 v[34:49], v[170:173], v[62:65], v[34:49]
	s_waitcnt lgkmcnt(10)
	v_mfma_f32_32x32x16_bf16 v[34:49], v[174:177], v[206:209], v[34:49]
	s_waitcnt lgkmcnt(8)
	v_mfma_f32_32x32x16_bf16 v[34:49], v[178:181], v[210:213], v[34:49]
	ds_read_b64_tr_b16 v[206:207], v0 offset:1536
	ds_read_b64_tr_b16 v[208:209], v0 offset:3584
	ds_read_b64_tr_b16 v[210:211], v0 offset:5632
	ds_read_b64_tr_b16 v[212:213], v0 offset:7680
	ds_read_b64_tr_b16 v[230:231], v0 offset:9728
	ds_read_b64_tr_b16 v[232:233], v0 offset:11776
	ds_read_b64_tr_b16 v[234:235], v0 offset:13824
	ds_read_b64_tr_b16 v[236:237], v0 offset:15872
	s_waitcnt lgkmcnt(14)
	v_mfma_f32_32x32x16_bf16 v[50:65], v[166:169], v[214:217], v[2:17]
	s_waitcnt lgkmcnt(12)
	v_mfma_f32_32x32x16_bf16 v[50:65], v[170:173], v[218:221], v[50:65]
	s_waitcnt lgkmcnt(10)
	v_mfma_f32_32x32x16_bf16 v[50:65], v[174:177], v[222:225], v[50:65]
	s_waitcnt lgkmcnt(8)
	v_mfma_f32_32x32x16_bf16 v[50:65], v[178:181], v[226:229], v[50:65]
	s_waitcnt lgkmcnt(6)
	v_mfma_f32_32x32x16_bf16 v[2:17], v[166:169], v[206:209], v[2:17]
	s_waitcnt lgkmcnt(4)
	v_mfma_f32_32x32x16_bf16 v[2:17], v[170:173], v[210:213], v[2:17]
	s_waitcnt lgkmcnt(2)
	v_mfma_f32_32x32x16_bf16 v[2:17], v[174:177], v[230:233], v[2:17]
	s_waitcnt lgkmcnt(0)
	v_mfma_f32_32x32x16_bf16 v[2:17], v[178:181], v[234:237], v[2:17]
	s_waitcnt lgkmcnt(0)
	s_barrier
; __device__ __forceinline__ int crow(int r, int hi) { return (r & 3) + 8 * (r >> 2) + 4 * hi; }
; __device__ __forceinline__ void cmask(f32x16& p0, f32x16& p1, int t, int qrel, int hi) {
;     const float ninf = -__builtin_inff();
; #pragma unroll
;     for (int r = 0; r < 16; ++r) { const int k0 = 64 * t + crow(r, hi); if (k0 > qrel) p0[r] = ninf; if (k0 + 32 > qrel) p1[r] = ninf; }
; }
	s_cmp_lt_i32 s82, 4
	s_cselect_b64 s[0:1], -1, 0
	s_and_b64 s[0:1], s[66:67], s[0:1]
	s_andn2_b64 vcc, exec, s[0:1]
	s_cbranch_vccnz .LBB0_805
	v_or_b32_e32 v166, 0x60, v196
	v_or_b32_e32 v0, 64, v196
	v_cmp_le_i32_e32 vcc, v166, v203
	s_nop 1
	v_cndmask_b32_e32 v66, v190, v66, vcc
	v_cmp_lt_i32_e32 vcc, v0, v203
	s_nop 1
	v_cndmask_b32_e32 v83, v190, v83, vcc
	v_cmp_le_i32_e32 vcc, v0, v203
	v_or_b32_e32 v0, 0x61, v196
	s_nop 0
	v_cndmask_b32_e32 v82, v190, v82, vcc
	v_cmp_le_i32_e32 vcc, v0, v203
	v_or_b32_e32 v0, 0x42, v196
	s_nop 0
	v_cndmask_b32_e32 v67, v190, v67, vcc
	v_cmp_le_i32_e32 vcc, v0, v203
	v_or_b32_e32 v0, 0x62, v196
	s_nop 0
	v_cndmask_b32_e32 v84, v190, v84, vcc
	v_cmp_le_i32_e32 vcc, v0, v203
	v_or_b32_e32 v0, 0x43, v196
	s_nop 0
	v_cndmask_b32_e32 v68, v190, v68, vcc
	v_cmp_le_i32_e32 vcc, v0, v203
	v_or_b32_e32 v0, 0x63, v196
	s_nop 0
	v_cndmask_b32_e32 v85, v190, v85, vcc
	v_cmp_le_i32_e32 vcc, v0, v203
	v_or_b32_e32 v0, 0x48, v196
	s_nop 0
	v_cndmask_b32_e32 v69, v190, v69, vcc
	v_cmp_le_i32_e32 vcc, v0, v203
	v_or_b32_e32 v0, 0x68, v196
	s_nop 0
	v_cndmask_b32_e32 v86, v190, v86, vcc
	v_cmp_le_i32_e32 vcc, v0, v203
	v_or_b32_e32 v0, 0x49, v196
	s_nop 0
	v_cndmask_b32_e32 v70, v190, v70, vcc
	v_cmp_le_i32_e32 vcc, v0, v203
	v_or_b32_e32 v0, 0x69, v196
	s_nop 0
	v_cndmask_b32_e32 v87, v190, v87, vcc
	v_cmp_le_i32_e32 vcc, v0, v203
	v_or_b32_e32 v0, 0x4a, v196
	s_nop 0
	v_cndmask_b32_e32 v71, v190, v71, vcc
	v_cmp_le_i32_e32 vcc, v0, v203
	v_or_b32_e32 v0, 0x6a, v196
	s_nop 0
	v_cndmask_b32_e32 v88, v190, v88, vcc
	v_cmp_le_i32_e32 vcc, v0, v203
	v_or_b32_e32 v0, 0x4b, v196
	s_nop 0
	v_cndmask_b32_e32 v72, v190, v72, vcc
	v_cmp_le_i32_e32 vcc, v0, v203
	v_or_b32_e32 v0, 0x6b, v196
	s_nop 0
	v_cndmask_b32_e32 v89, v190, v89, vcc
	v_cmp_le_i32_e32 vcc, v0, v203
	v_or_b32_e32 v0, 0x50, v196
	s_nop 0
	v_cndmask_b32_e32 v73, v190, v73, vcc
	v_cmp_le_i32_e32 vcc, v0, v203
	v_or_b32_e32 v0, 0x70, v196
	s_nop 0
	v_cndmask_b32_e32 v90, v190, v90, vcc
	v_cmp_le_i32_e32 vcc, v0, v203
	v_or_b32_e32 v0, 0x51, v196
	s_nop 0
	v_cndmask_b32_e32 v74, v190, v74, vcc
	v_cmp_le_i32_e32 vcc, v0, v203
	v_or_b32_e32 v0, 0x71, v196
	s_nop 0
	v_cndmask_b32_e32 v91, v190, v91, vcc
	v_cmp_le_i32_e32 vcc, v0, v203
	v_or_b32_e32 v0, 0x52, v196
	s_nop 0
	v_cndmask_b32_e32 v75, v190, v75, vcc
	v_cmp_le_i32_e32 vcc, v0, v203
	v_or_b32_e32 v0, 0x72, v196
	s_nop 0
	v_cndmask_b32_e32 v92, v190, v92, vcc
	v_cmp_le_i32_e32 vcc, v0, v203
	v_or_b32_e32 v0, 0x53, v196
	s_nop 0
	v_cndmask_b32_e32 v76, v190, v76, vcc
	v_cmp_le_i32_e32 vcc, v0, v203
	v_or_b32_e32 v0, 0x73, v196
	s_nop 0
	v_cndmask_b32_e32 v93, v190, v93, vcc
	v_cmp_le_i32_e32 vcc, v0, v203
	v_or_b32_e32 v0, 0x58, v196
	s_nop 0
	v_cndmask_b32_e32 v77, v190, v77, vcc
	v_cmp_le_i32_e32 vcc, v0, v203
	v_or_b32_e32 v0, 0x78, v196
	s_nop 0
	v_cndmask_b32_e32 v94, v190, v94, vcc
	v_cmp_le_i32_e32 vcc, v0, v203
	v_or_b32_e32 v0, 0x59, v196
	s_nop 0
	v_cndmask_b32_e32 v78, v190, v78, vcc
	v_cmp_le_i32_e32 vcc, v0, v203
	v_or_b32_e32 v0, 0x79, v196
	s_nop 0
	v_cndmask_b32_e32 v95, v190, v95, vcc
	v_cmp_le_i32_e32 vcc, v0, v203
	v_or_b32_e32 v0, 0x5a, v196
	s_nop 0
	v_cndmask_b32_e32 v79, v190, v79, vcc
	v_cmp_le_i32_e32 vcc, v0, v203
	v_or_b32_e32 v0, 0x7a, v196
	s_nop 0
	v_cndmask_b32_e32 v96, v190, v96, vcc
	v_cmp_le_i32_e32 vcc, v0, v203
	v_or_b32_e32 v0, 0x5b, v196
	s_nop 0
	v_cndmask_b32_e32 v80, v190, v80, vcc
	v_cmp_le_i32_e32 vcc, v0, v203
	v_or_b32_e32 v0, 0x7b, v196
	s_nop 0
	v_cndmask_b32_e32 v97, v190, v97, vcc
	v_cmp_le_i32_e32 vcc, v0, v203
	s_nop 1
	v_cndmask_b32_e32 v81, v190, v81, vcc

; #define ATT_SBAR() __builtin_amdgcn_sched_barrier(0)
; #define QP_LD(d, s) do { ka[s] = *reinterpret_cast<const bf16x8*>(r0 + (d) * 32); kb[s] = *reinterpret_cast<const bf16x8*>(r1 + (d) * 32); } while (0)
; #define ATT_TRB(vb, off) __builtin_amdgcn_ds_read_tr16_b64_v4i16((LAS s16x4*)(unsigned)((vb) + (off)))
; #define QP_LD(d, s) do { ka[s] = *reinterpret_cast<const bf16x8*>(r0 + (d) * 32); kb[s] = *reinterpret_cast<const bf16x8*>(r1 + (d) * 32); } while (0)
; template <int DK> __device__ __forceinline__ void qkt_pipe_pv(f32x16& p0, f32x16& p1, const char* Ks, const bf16x8* qr, int r32, int hi, int vb, s16x4 (&F)[8]) {
;     constexpr int ND = DK / 16, KR = DK * 2 + 16;
;     const char* r0 = Ks + ATT_KSWZ(r32, hi * 16, KR); const char* r1 = Ks + ATT_KSWZ(32 + r32, hi * 16, KR);
;     bf16x8 ka[3], kb[3];
;     ...
;     QP_LD(0, 0); QP_LD(1, 1); QP_LD(2, 2); ATT_SBAR();
;     p0 = f32x16{}; p1 = f32x16{};
;     __builtin_amdgcn_s_setprio(1);
; #pragma unroll
;     for (int d0 = 0; d0 < ND; ++d0) {
;         p0 = __builtin_amdgcn_mfma_f32_32x32x16_bf16(ka[d0 % 3], qr[d0], p0, 0, 0, 0);
;         p1 = __builtin_amdgcn_mfma_f32_32x32x16_bf16(kb[d0 % 3], qr[d0], p1, 0, 0, 0);
;         if (d0 + 3 < ND) QP_LD(d0 + 3, d0 % 3);
;         if (d0 == ND - 3) { F[0] = ATT_TRB(vb, v_rd_off(0, 0, 0)); F[1] = ATT_TRB(vb, v_rd_off(0, 0, 1)); F[2] = ATT_TRB(vb, v_rd_off(0, 1, 0)); F[3] = ATT_TRB(vb, v_rd_off(0, 1, 1)); }
;         if (d0 == ND - 2) { F[4] = ATT_TRB(vb, v_rd_off(0, 2, 0)); F[5] = ATT_TRB(vb, v_rd_off(0, 2, 1)); F[6] = ATT_TRB(vb, v_rd_off(0, 3, 0)); F[7] = ATT_TRB(vb, v_rd_off(0, 3, 1)); }
;         ATT_SBAR(); }
;     __builtin_amdgcn_s_setprio(0);
;     ...
; }
; __device__ __forceinline__ void pv_d0_pre(f32x16* o, int vb, bf16x8 pa0, bf16x8 pa1, bf16x8 pa2, bf16x8 pa3, s16x4 (&F)[8]) {
;     s16x4 G[8];
;     ...
;     PVB_RD(1, G); ATT_SBAR(); PVB_MM(0, F); ATT_SBAR();
;     PVB_RD(2, F); ATT_SBAR(); PVB_MM(1, G); ATT_SBAR();
;     PVB_RD(3, G); ATT_SBAR(); PVB_MM(2, F); ATT_SBAR();
;     PVB_MM(3, G);
;     ...
; }
.LBB0_819:
	ds_read_b128 v[66:69], v195 offset:32768
	ds_read_b128 v[204:207], v195 offset:32800
	ds_read_b128 v[70:73], v195 offset:45568
	ds_read_b128 v[208:211], v195 offset:32832
	ds_read_b128 v[212:215], v195 offset:45600
	ds_read_b128 v[216:219], v195 offset:45632
	s_waitcnt lgkmcnt(5)
	v_mfma_f32_32x32x16_bf16 v[82:97], v[66:69], v[98:101], 0
	ds_read_b128 v[220:223], v195 offset:32864
	ds_read_b128 v[224:227], v195 offset:45664
	s_waitcnt lgkmcnt(5)
	v_mfma_f32_32x32x16_bf16 v[66:81], v[70:73], v[98:101], 0
	v_mfma_f32_32x32x16_bf16 v[82:97], v[204:207], v[102:105], v[82:97]
	ds_read_b128 v[204:207], v195 offset:32896
	ds_read_b128 v[228:231], v195 offset:45696
	s_waitcnt lgkmcnt(5)
	v_mfma_f32_32x32x16_bf16 v[66:81], v[212:215], v[102:105], v[66:81]
	v_mfma_f32_32x32x16_bf16 v[82:97], v[208:211], v[106:109], v[82:97]
	ds_read_b128 v[208:211], v195 offset:32928
	ds_read_b128 v[212:215], v195 offset:45728
	s_waitcnt lgkmcnt(6)
	v_mfma_f32_32x32x16_bf16 v[66:81], v[216:219], v[106:109], v[66:81]
	s_waitcnt lgkmcnt(5)
	v_mfma_f32_32x32x16_bf16 v[82:97], v[220:223], v[110:113], v[82:97]
	ds_read_b128 v[216:219], v195 offset:32960
	ds_read_b128 v[220:223], v195 offset:45760
	s_waitcnt lgkmcnt(6)
	v_mfma_f32_32x32x16_bf16 v[66:81], v[224:227], v[110:113], v[66:81]
	s_waitcnt lgkmcnt(5)
	v_mfma_f32_32x32x16_bf16 v[82:97], v[204:207], v[114:117], v[82:97]
	ds_read_b128 v[204:207], v195 offset:32992
	ds_read_b128 v[224:227], v195 offset:45792
	s_waitcnt lgkmcnt(6)
	v_mfma_f32_32x32x16_bf16 v[66:81], v[228:231], v[114:117], v[66:81]
	s_waitcnt lgkmcnt(5)
	v_mfma_f32_32x32x16_bf16 v[82:97], v[208:211], v[118:121], v[82:97]
	ds_read_b128 v[208:211], v195 offset:33024
	ds_read_b128 v[228:231], v195 offset:45824
	s_waitcnt lgkmcnt(6)
	v_mfma_f32_32x32x16_bf16 v[66:81], v[212:215], v[118:121], v[66:81]
	s_waitcnt lgkmcnt(5)
	v_mfma_f32_32x32x16_bf16 v[82:97], v[216:219], v[122:125], v[82:97]
	ds_read_b128 v[212:215], v195 offset:33056
	ds_read_b128 v[216:219], v195 offset:45856
	s_waitcnt lgkmcnt(6)
	v_mfma_f32_32x32x16_bf16 v[66:81], v[220:223], v[122:125], v[66:81]
	s_waitcnt lgkmcnt(5)
	v_mfma_f32_32x32x16_bf16 v[82:97], v[204:207], v[126:129], v[82:97]
	ds_read_b128 v[204:207], v195 offset:33088
	ds_read_b128 v[220:223], v195 offset:45888
	s_waitcnt lgkmcnt(6)
	v_mfma_f32_32x32x16_bf16 v[66:81], v[224:227], v[126:129], v[66:81]
	s_waitcnt lgkmcnt(5)
	v_mfma_f32_32x32x16_bf16 v[82:97], v[208:211], v[130:133], v[82:97]
	ds_read_b128 v[208:211], v195 offset:33120
	ds_read_b128 v[224:227], v195 offset:45920
	s_waitcnt lgkmcnt(6)
	v_mfma_f32_32x32x16_bf16 v[66:81], v[228:231], v[130:133], v[66:81]
	s_waitcnt lgkmcnt(5)
	v_mfma_f32_32x32x16_bf16 v[82:97], v[212:215], v[158:161], v[82:97]
	ds_read_b64_tr_b16 v[212:213], v197 offset:16384
	ds_read_b64_tr_b16 v[214:215], v197 offset:18432
	ds_read_b64_tr_b16 v[228:229], v197 offset:20480
	ds_read_b64_tr_b16 v[230:231], v197 offset:22528
	s_waitcnt lgkmcnt(8)
	v_mfma_f32_32x32x16_bf16 v[66:81], v[216:219], v[158:161], v[66:81]
	s_waitcnt lgkmcnt(7)
	v_mfma_f32_32x32x16_bf16 v[82:97], v[204:207], v[134:137], v[82:97]
	ds_read_b64_tr_b16 v[204:205], v197 offset:24576
	ds_read_b64_tr_b16 v[206:207], v197 offset:26624
	ds_read_b64_tr_b16 v[216:217], v197 offset:28672
	ds_read_b64_tr_b16 v[218:219], v197 offset:30720
	s_waitcnt lgkmcnt(10)
	v_mfma_f32_32x32x16_bf16 v[66:81], v[220:223], v[134:137], v[66:81]
	s_waitcnt lgkmcnt(9)
	v_mfma_f32_32x32x16_bf16 v[82:97], v[208:211], v[162:165], v[82:97]
	s_waitcnt lgkmcnt(8)
	v_mfma_f32_32x32x16_bf16 v[66:81], v[224:227], v[162:165], v[66:81]
	ds_read_b64_tr_b16 v[208:209], v197 offset:16896
	ds_read_b64_tr_b16 v[210:211], v197 offset:18944
	ds_read_b64_tr_b16 v[220:221], v197 offset:20992
	ds_read_b64_tr_b16 v[222:223], v197 offset:23040
	ds_read_b64_tr_b16 v[224:225], v197 offset:25088
	ds_read_b64_tr_b16 v[226:227], v197 offset:27136
	ds_read_b64_tr_b16 v[232:233], v197 offset:29184
	ds_read_b64_tr_b16 v[234:235], v197 offset:31232
	s_waitcnt lgkmcnt(14)
	v_mfma_f32_32x32x16_bf16 v[18:33], v[166:169], v[212:215], v[18:33]
	s_waitcnt lgkmcnt(12)
	v_mfma_f32_32x32x16_bf16 v[18:33], v[170:173], v[228:231], v[18:33]
	s_waitcnt lgkmcnt(10)
	v_mfma_f32_32x32x16_bf16 v[18:33], v[174:177], v[204:207], v[18:33]
	s_waitcnt lgkmcnt(8)
	v_mfma_f32_32x32x16_bf16 v[18:33], v[178:181], v[216:219], v[18:33]
	ds_read_b64_tr_b16 v[204:205], v197 offset:17408
	ds_read_b64_tr_b16 v[206:207], v197 offset:19456
	ds_read_b64_tr_b16 v[212:213], v197 offset:21504
	ds_read_b64_tr_b16 v[214:215], v197 offset:23552
	ds_read_b64_tr_b16 v[216:217], v197 offset:25600
	ds_read_b64_tr_b16 v[218:219], v197 offset:27648
	ds_read_b64_tr_b16 v[228:229], v197 offset:29696
	ds_read_b64_tr_b16 v[230:231], v197 offset:31744
	s_waitcnt lgkmcnt(14)
	v_mfma_f32_32x32x16_bf16 v[34:49], v[166:169], v[208:211], v[34:49]
	s_waitcnt lgkmcnt(12)
	v_mfma_f32_32x32x16_bf16 v[34:49], v[170:173], v[220:223], v[34:49]
	s_waitcnt lgkmcnt(10)
	v_mfma_f32_32x32x16_bf16 v[34:49], v[174:177], v[224:227], v[34:49]
	s_waitcnt lgkmcnt(8)
	v_mfma_f32_32x32x16_bf16 v[34:49], v[178:181], v[232:235], v[34:49]
	ds_read_b64_tr_b16 v[208:209], v197 offset:17920
	ds_read_b64_tr_b16 v[210:211], v197 offset:19968
	ds_read_b64_tr_b16 v[220:221], v197 offset:22016
	ds_read_b64_tr_b16 v[222:223], v197 offset:24064
	ds_read_b64_tr_b16 v[224:225], v197 offset:26112
	ds_read_b64_tr_b16 v[226:227], v197 offset:28160
	ds_read_b64_tr_b16 v[232:233], v197 offset:30208
	ds_read_b64_tr_b16 v[234:235], v197 offset:32256
	s_waitcnt lgkmcnt(14)
	v_mfma_f32_32x32x16_bf16 v[50:65], v[166:169], v[204:207], v[50:65]
	s_waitcnt lgkmcnt(12)
	v_mfma_f32_32x32x16_bf16 v[50:65], v[170:173], v[212:215], v[50:65]
	s_waitcnt lgkmcnt(10)
	v_mfma_f32_32x32x16_bf16 v[50:65], v[174:177], v[216:219], v[50:65]
	s_waitcnt lgkmcnt(8)
	v_mfma_f32_32x32x16_bf16 v[50:65], v[178:181], v[228:231], v[50:65]
	s_waitcnt lgkmcnt(6)
	v_mfma_f32_32x32x16_bf16 v[2:17], v[166:169], v[208:211], v[2:17]
	s_waitcnt lgkmcnt(4)
	v_mfma_f32_32x32x16_bf16 v[2:17], v[170:173], v[220:223], v[2:17]
	s_waitcnt lgkmcnt(2)
	v_mfma_f32_32x32x16_bf16 v[2:17], v[174:177], v[224:227], v[2:17]
	s_waitcnt lgkmcnt(0)
	v_mfma_f32_32x32x16_bf16 v[2:17], v[178:181], v[232:235], v[2:17]
	s_waitcnt lgkmcnt(0)
	s_barrier
; __device__ __forceinline__ int crow(int r, int hi) { return (r & 3) + 8 * (r >> 2) + 4 * hi; }
; __device__ __forceinline__ void cmask(f32x16& p0, f32x16& p1, int t, int qrel, int hi) {
;     const float ninf = -__builtin_inff();
; #pragma unroll
;     for (int r = 0; r < 16; ++r) { const int k0 = 64 * t + crow(r, hi); if (k0 > qrel) p0[r] = ninf; if (k0 + 32 > qrel) p1[r] = ninf; }
; }
	s_add_i32 s8, s90, s86
	s_cmp_lt_i32 s8, 0
	s_cbranch_scc1 .LBB0_822
	s_sub_i32 s0, s58, 64
	s_cmp_le_i32 s0, s83
	s_cbranch_scc1 .LBB0_822
	v_add_u32_e32 v0, s58, v196
	v_add_u32_e32 v167, 0xffffffa1, v0
	v_add_u32_e32 v166, 0xffffff81, v0
	v_cmp_le_i32_e32 vcc, v167, v200
	s_nop 1
	v_cndmask_b32_e32 v66, v190, v66, vcc
	v_cmp_lt_i32_e32 vcc, v166, v200
	s_nop 1
	v_cndmask_b32_e32 v83, v190, v83, vcc
	v_cmp_le_i32_e32 vcc, v166, v200
	v_add_u32_e32 v166, 0xffffffa2, v0
	s_nop 0
	v_cndmask_b32_e32 v82, v190, v82, vcc
	v_cmp_le_i32_e32 vcc, v166, v200
	v_add_u32_e32 v166, 0xffffff83, v0
	s_nop 0
	v_cndmask_b32_e32 v67, v190, v67, vcc
	v_cmp_le_i32_e32 vcc, v166, v200
	v_add_u32_e32 v166, 0xffffffa3, v0
	s_nop 0
	v_cndmask_b32_e32 v84, v190, v84, vcc
	v_cmp_le_i32_e32 vcc, v166, v200
	v_add_u32_e32 v166, 0xffffff84, v0
	s_nop 0
	v_cndmask_b32_e32 v68, v190, v68, vcc
	v_cmp_le_i32_e32 vcc, v166, v200
	v_add_u32_e32 v166, 0xffffffa4, v0
	s_nop 0
	v_cndmask_b32_e32 v85, v190, v85, vcc
	v_cmp_le_i32_e32 vcc, v166, v200
	v_add_u32_e32 v166, 0xffffff89, v0
	s_nop 0
	v_cndmask_b32_e32 v69, v190, v69, vcc
	v_cmp_le_i32_e32 vcc, v166, v200
	v_add_u32_e32 v166, 0xffffffa9, v0
	s_nop 0
	v_cndmask_b32_e32 v86, v190, v86, vcc
	v_cmp_le_i32_e32 vcc, v166, v200
	v_add_u32_e32 v166, 0xffffff8a, v0
	s_nop 0
	v_cndmask_b32_e32 v70, v190, v70, vcc
	v_cmp_le_i32_e32 vcc, v166, v200
	v_add_u32_e32 v166, 0xffffffaa, v0
	s_nop 0
	v_cndmask_b32_e32 v87, v190, v87, vcc
	v_cmp_le_i32_e32 vcc, v166, v200
	v_add_u32_e32 v166, 0xffffff8b, v0
	s_nop 0
	v_cndmask_b32_e32 v71, v190, v71, vcc
	v_cmp_le_i32_e32 vcc, v166, v200
	v_add_u32_e32 v166, 0xffffffab, v0
	s_nop 0
	v_cndmask_b32_e32 v88, v190, v88, vcc
	v_cmp_le_i32_e32 vcc, v166, v200
	v_add_u32_e32 v166, 0xffffff8c, v0
	s_nop 0
	v_cndmask_b32_e32 v72, v190, v72, vcc
	v_cmp_le_i32_e32 vcc, v166, v200
	v_add_u32_e32 v166, 0xffffffac, v0
	s_nop 0
	v_cndmask_b32_e32 v89, v190, v89, vcc
	v_cmp_le_i32_e32 vcc, v166, v200
	v_add_u32_e32 v166, 0xffffff91, v0
	s_nop 0
	v_cndmask_b32_e32 v73, v190, v73, vcc
	v_cmp_le_i32_e32 vcc, v166, v200
	v_add_u32_e32 v166, 0xffffffb1, v0
	s_nop 0
	v_cndmask_b32_e32 v90, v190, v90, vcc
	v_cmp_le_i32_e32 vcc, v166, v200
	v_add_u32_e32 v166, 0xffffff92, v0
	s_nop 0
	v_cndmask_b32_e32 v74, v190, v74, vcc
	v_cmp_le_i32_e32 vcc, v166, v200
	v_add_u32_e32 v166, 0xffffffb2, v0
	s_nop 0
	v_cndmask_b32_e32 v91, v190, v91, vcc
	v_cmp_le_i32_e32 vcc, v166, v200
	v_add_u32_e32 v166, 0xffffff93, v0
	s_nop 0
	v_cndmask_b32_e32 v75, v190, v75, vcc
	v_cmp_le_i32_e32 vcc, v166, v200
	v_add_u32_e32 v166, 0xffffffb3, v0
	s_nop 0
	v_cndmask_b32_e32 v92, v190, v92, vcc
	v_cmp_le_i32_e32 vcc, v166, v200
	v_add_u32_e32 v166, 0xffffff94, v0
	s_nop 0
	v_cndmask_b32_e32 v76, v190, v76, vcc
	v_cmp_le_i32_e32 vcc, v166, v200
	v_add_u32_e32 v166, 0xffffffb4, v0
	s_nop 0
	v_cndmask_b32_e32 v93, v190, v93, vcc
	v_cmp_le_i32_e32 vcc, v166, v200
	v_add_u32_e32 v166, 0xffffff99, v0
	s_nop 0
	v_cndmask_b32_e32 v77, v190, v77, vcc
	v_cmp_le_i32_e32 vcc, v166, v200
	v_add_u32_e32 v166, 0xffffffb9, v0
	s_nop 0
	v_cndmask_b32_e32 v94, v190, v94, vcc
	v_cmp_le_i32_e32 vcc, v166, v200
	v_add_u32_e32 v166, 0xffffff9a, v0
	s_nop 0
	v_cndmask_b32_e32 v78, v190, v78, vcc
	v_cmp_le_i32_e32 vcc, v166, v200
	v_add_u32_e32 v166, 0xffffffba, v0
	s_nop 0
	v_cndmask_b32_e32 v95, v190, v95, vcc
	v_cmp_le_i32_e32 vcc, v166, v200
	v_add_u32_e32 v166, 0xffffff9b, v0
	s_nop 0
	v_cndmask_b32_e32 v79, v190, v79, vcc
	v_cmp_le_i32_e32 vcc, v166, v200
	v_add_u32_e32 v166, 0xffffffbb, v0
	s_nop 0
	v_cndmask_b32_e32 v96, v190, v96, vcc
	v_cmp_le_i32_e32 vcc, v166, v200
	v_add_u32_e32 v166, 0xffffff9c, v0
	v_add_u32_e32 v0, 0xffffffbc, v0
	v_cndmask_b32_e32 v80, v190, v80, vcc
	v_cmp_le_i32_e32 vcc, v166, v200
	s_nop 1
	v_cndmask_b32_e32 v97, v190, v97, vcc
	v_cmp_le_i32_e32 vcc, v0, v200
	s_nop 1
	v_cndmask_b32_e32 v81, v190, v81, vcc

; #define ATT_SBAR() __builtin_amdgcn_sched_barrier(0)
; #define QP_LD(d, s) do { ka[s] = *reinterpret_cast<const bf16x8*>(r0 + (d) * 32); kb[s] = *reinterpret_cast<const bf16x8*>(r1 + (d) * 32); } while (0)
; #define ATT_TRB(vb, off) __builtin_amdgcn_ds_read_tr16_b64_v4i16((LAS s16x4*)(unsigned)((vb) + (off)))
; #define QP_LD(d, s) do { ka[s] = *reinterpret_cast<const bf16x8*>(r0 + (d) * 32); kb[s] = *reinterpret_cast<const bf16x8*>(r1 + (d) * 32); } while (0)
; template <int DK> __device__ __forceinline__ void qkt_pipe_pv(f32x16& p0, f32x16& p1, const char* Ks, const bf16x8* qr, int r32, int hi, int vb, s16x4 (&F)[8]) {
;     constexpr int ND = DK / 16, KR = DK * 2 + 16;
;     const char* r0 = Ks + ATT_KSWZ(r32, hi * 16, KR); const char* r1 = Ks + ATT_KSWZ(32 + r32, hi * 16, KR);
;     bf16x8 ka[3], kb[3];
;     ...
;     QP_LD(0, 0); QP_LD(1, 1); QP_LD(2, 2); ATT_SBAR();
;     p0 = f32x16{}; p1 = f32x16{};
;     __builtin_amdgcn_s_setprio(1);
; #pragma unroll
;     for (int d0 = 0; d0 < ND; ++d0) {
;         p0 = __builtin_amdgcn_mfma_f32_32x32x16_bf16(ka[d0 % 3], qr[d0], p0, 0, 0, 0);
;         p1 = __builtin_amdgcn_mfma_f32_32x32x16_bf16(kb[d0 % 3], qr[d0], p1, 0, 0, 0);
;         if (d0 + 3 < ND) QP_LD(d0 + 3, d0 % 3);
;         if (d0 == ND - 3) { F[0] = ATT_TRB(vb, v_rd_off(0, 0, 0)); F[1] = ATT_TRB(vb, v_rd_off(0, 0, 1)); F[2] = ATT_TRB(vb, v_rd_off(0, 1, 0)); F[3] = ATT_TRB(vb, v_rd_off(0, 1, 1)); }
;         if (d0 == ND - 2) { F[4] = ATT_TRB(vb, v_rd_off(0, 2, 0)); F[5] = ATT_TRB(vb, v_rd_off(0, 2, 1)); F[6] = ATT_TRB(vb, v_rd_off(0, 3, 0)); F[7] = ATT_TRB(vb, v_rd_off(0, 3, 1)); }
;         ATT_SBAR(); }
;     __builtin_amdgcn_s_setprio(0);
;     ...
; }
; __device__ __forceinline__ void pv_d0_pre(f32x16* o, int vb, bf16x8 pa0, bf16x8 pa1, bf16x8 pa2, bf16x8 pa3, s16x4 (&F)[8]) {
;     s16x4 G[8];
;     ...
;     PVB_RD(1, G); ATT_SBAR(); PVB_MM(0, F); ATT_SBAR();
;     PVB_RD(2, F); ATT_SBAR(); PVB_MM(1, G); ATT_SBAR();
;     PVB_RD(3, G); ATT_SBAR(); PVB_MM(2, F); ATT_SBAR();
;     PVB_MM(3, G);
;     ...
; }
.LBB0_834:
	s_waitcnt lgkmcnt(0)
	s_barrier
	ds_read_b128 v[66:69], v195 offset:58368
	ds_read_b128 v[206:209], v195 offset:58400
	ds_read_b128 v[70:73], v198 offset:12800
	ds_read_b128 v[210:213], v195 offset:58432
	ds_read_b128 v[214:217], v198 offset:12832
	ds_read_b128 v[218:221], v198 offset:12864
	s_waitcnt lgkmcnt(5)
	v_mfma_f32_32x32x16_bf16 v[82:97], v[66:69], v[98:101], 0
	ds_read_b128 v[222:225], v195 offset:58464
	ds_read_b128 v[226:229], v198 offset:12896
	s_waitcnt lgkmcnt(5)
	v_mfma_f32_32x32x16_bf16 v[66:81], v[70:73], v[98:101], 0
	v_mfma_f32_32x32x16_bf16 v[82:97], v[206:209], v[102:105], v[82:97]
	ds_read_b128 v[206:209], v195 offset:58496
	ds_read_b128 v[230:233], v198 offset:12928
	s_waitcnt lgkmcnt(5)
	v_mfma_f32_32x32x16_bf16 v[66:81], v[214:217], v[102:105], v[66:81]
	v_mfma_f32_32x32x16_bf16 v[82:97], v[210:213], v[106:109], v[82:97]
	ds_read_b128 v[210:213], v195 offset:58528
	ds_read_b128 v[214:217], v198 offset:12960
	s_waitcnt lgkmcnt(6)
	v_mfma_f32_32x32x16_bf16 v[66:81], v[218:221], v[106:109], v[66:81]
	s_waitcnt lgkmcnt(5)
	v_mfma_f32_32x32x16_bf16 v[82:97], v[222:225], v[110:113], v[82:97]
	ds_read_b128 v[218:221], v195 offset:58560
	ds_read_b128 v[222:225], v198 offset:12992
	s_waitcnt lgkmcnt(6)
	v_mfma_f32_32x32x16_bf16 v[66:81], v[226:229], v[110:113], v[66:81]
	s_waitcnt lgkmcnt(5)
	v_mfma_f32_32x32x16_bf16 v[82:97], v[206:209], v[114:117], v[82:97]
	ds_read_b128 v[206:209], v195 offset:58592
	ds_read_b128 v[226:229], v198 offset:13024
	s_waitcnt lgkmcnt(6)
	v_mfma_f32_32x32x16_bf16 v[66:81], v[230:233], v[114:117], v[66:81]
	s_waitcnt lgkmcnt(5)
	v_mfma_f32_32x32x16_bf16 v[82:97], v[210:213], v[118:121], v[82:97]
	ds_read_b128 v[210:213], v195 offset:58624
	ds_read_b128 v[230:233], v198 offset:13056
	s_waitcnt lgkmcnt(6)
	v_mfma_f32_32x32x16_bf16 v[66:81], v[214:217], v[118:121], v[66:81]
	s_waitcnt lgkmcnt(5)
	v_mfma_f32_32x32x16_bf16 v[82:97], v[218:221], v[122:125], v[82:97]
	ds_read_b128 v[214:217], v195 offset:58656
	ds_read_b128 v[218:221], v198 offset:13088
	s_waitcnt lgkmcnt(6)
	v_mfma_f32_32x32x16_bf16 v[66:81], v[222:225], v[122:125], v[66:81]
	s_waitcnt lgkmcnt(5)
	v_mfma_f32_32x32x16_bf16 v[82:97], v[206:209], v[126:129], v[82:97]
	ds_read_b128 v[206:209], v195 offset:58688
	ds_read_b128 v[222:225], v198 offset:13120
	s_waitcnt lgkmcnt(6)
	v_mfma_f32_32x32x16_bf16 v[66:81], v[226:229], v[126:129], v[66:81]
	s_waitcnt lgkmcnt(5)
	v_mfma_f32_32x32x16_bf16 v[82:97], v[210:213], v[130:133], v[82:97]
	ds_read_b128 v[210:213], v195 offset:58720
	ds_read_b128 v[226:229], v198 offset:13152
	s_waitcnt lgkmcnt(6)
	v_mfma_f32_32x32x16_bf16 v[66:81], v[230:233], v[130:133], v[66:81]
	s_waitcnt lgkmcnt(5)
	v_mfma_f32_32x32x16_bf16 v[82:97], v[214:217], v[158:161], v[82:97]
	ds_read_b64_tr_b16 v[214:215], v197
	ds_read_b64_tr_b16 v[216:217], v197 offset:2048
	ds_read_b64_tr_b16 v[230:231], v197 offset:4096
	ds_read_b64_tr_b16 v[232:233], v197 offset:6144
	s_waitcnt lgkmcnt(8)
	v_mfma_f32_32x32x16_bf16 v[66:81], v[218:221], v[158:161], v[66:81]
	s_waitcnt lgkmcnt(7)
	v_mfma_f32_32x32x16_bf16 v[82:97], v[206:209], v[134:137], v[82:97]
	ds_read_b64_tr_b16 v[206:207], v197 offset:8192
	ds_read_b64_tr_b16 v[208:209], v197 offset:10240
	ds_read_b64_tr_b16 v[218:219], v197 offset:12288
	ds_read_b64_tr_b16 v[220:221], v197 offset:14336
	s_waitcnt lgkmcnt(10)
	v_mfma_f32_32x32x16_bf16 v[66:81], v[222:225], v[134:137], v[66:81]
	s_waitcnt lgkmcnt(9)
	v_mfma_f32_32x32x16_bf16 v[82:97], v[210:213], v[162:165], v[82:97]
	s_waitcnt lgkmcnt(8)
	v_mfma_f32_32x32x16_bf16 v[66:81], v[226:229], v[162:165], v[66:81]
	ds_read_b64_tr_b16 v[210:211], v197 offset:512
	ds_read_b64_tr_b16 v[212:213], v197 offset:2560
	ds_read_b64_tr_b16 v[222:223], v197 offset:4608
	ds_read_b64_tr_b16 v[224:225], v197 offset:6656
	ds_read_b64_tr_b16 v[226:227], v197 offset:8704
	ds_read_b64_tr_b16 v[228:229], v197 offset:10752
	ds_read_b64_tr_b16 v[234:235], v197 offset:12800
	ds_read_b64_tr_b16 v[236:237], v197 offset:14848
	s_waitcnt lgkmcnt(14)
	v_mfma_f32_32x32x16_bf16 v[18:33], v[166:169], v[214:217], v[18:33]
	s_waitcnt lgkmcnt(12)
	v_mfma_f32_32x32x16_bf16 v[18:33], v[170:173], v[230:233], v[18:33]
	s_waitcnt lgkmcnt(10)
	v_mfma_f32_32x32x16_bf16 v[18:33], v[174:177], v[206:209], v[18:33]
	s_waitcnt lgkmcnt(8)
	v_mfma_f32_32x32x16_bf16 v[18:33], v[178:181], v[218:221], v[18:33]
	ds_read_b64_tr_b16 v[206:207], v197 offset:1024
	ds_read_b64_tr_b16 v[208:209], v197 offset:3072
	ds_read_b64_tr_b16 v[214:215], v197 offset:5120
	ds_read_b64_tr_b16 v[216:217], v197 offset:7168
	ds_read_b64_tr_b16 v[218:219], v197 offset:9216
	ds_read_b64_tr_b16 v[220:221], v197 offset:11264
	ds_read_b64_tr_b16 v[230:231], v197 offset:13312
	ds_read_b64_tr_b16 v[232:233], v197 offset:15360
	s_waitcnt lgkmcnt(14)
	v_mfma_f32_32x32x16_bf16 v[34:49], v[166:169], v[210:213], v[34:49]
	s_waitcnt lgkmcnt(12)
	v_mfma_f32_32x32x16_bf16 v[34:49], v[170:173], v[222:225], v[34:49]
	s_waitcnt lgkmcnt(10)
	v_mfma_f32_32x32x16_bf16 v[34:49], v[174:177], v[226:229], v[34:49]
	s_waitcnt lgkmcnt(8)
	v_mfma_f32_32x32x16_bf16 v[34:49], v[178:181], v[234:237], v[34:49]
	ds_read_b64_tr_b16 v[210:211], v197 offset:1536
	ds_read_b64_tr_b16 v[212:213], v197 offset:3584
	ds_read_b64_tr_b16 v[222:223], v197 offset:5632
	ds_read_b64_tr_b16 v[224:225], v197 offset:7680
	ds_read_b64_tr_b16 v[226:227], v197 offset:9728
	ds_read_b64_tr_b16 v[228:229], v197 offset:11776
	ds_read_b64_tr_b16 v[234:235], v197 offset:13824
	ds_read_b64_tr_b16 v[236:237], v197 offset:15872
	s_waitcnt lgkmcnt(14)
	v_mfma_f32_32x32x16_bf16 v[50:65], v[166:169], v[206:209], v[50:65]
	s_waitcnt lgkmcnt(12)
	v_mfma_f32_32x32x16_bf16 v[50:65], v[170:173], v[214:217], v[50:65]
	s_waitcnt lgkmcnt(10)
	v_mfma_f32_32x32x16_bf16 v[50:65], v[174:177], v[218:221], v[50:65]
	s_waitcnt lgkmcnt(8)
	v_mfma_f32_32x32x16_bf16 v[50:65], v[178:181], v[230:233], v[50:65]
	s_waitcnt lgkmcnt(6)
	v_mfma_f32_32x32x16_bf16 v[2:17], v[166:169], v[210:213], v[2:17]
	s_waitcnt lgkmcnt(4)
	v_mfma_f32_32x32x16_bf16 v[2:17], v[170:173], v[222:225], v[2:17]
	s_waitcnt lgkmcnt(2)
	v_mfma_f32_32x32x16_bf16 v[2:17], v[174:177], v[226:229], v[2:17]
	s_waitcnt lgkmcnt(0)
	v_mfma_f32_32x32x16_bf16 v[2:17], v[178:181], v[234:237], v[2:17]
	s_waitcnt lgkmcnt(0)
	s_barrier
; __device__ __forceinline__ int crow(int r, int hi) { return (r & 3) + 8 * (r >> 2) + 4 * hi; }
; __device__ __forceinline__ void cmask(f32x16& p0, f32x16& p1, int t, int qrel, int hi) {
;     const float ninf = -__builtin_inff();
; #pragma unroll
;     for (int r = 0; r < 16; ++r) { const int k0 = 64 * t + crow(r, hi); if (k0 > qrel) p0[r] = ninf; if (k0 + 32 > qrel) p1[r] = ninf; }
; }
	s_add_i32 s8, s8, 1
	s_cmp_lt_i32 s8, 0
	s_cbranch_scc1 .LBB0_837
	s_cmp_le_i32 s58, s83
	s_cbranch_scc1 .LBB0_837
	v_add_u32_e32 v0, s58, v196
	v_subrev_u32_e32 v167, 31, v0
	v_subrev_u32_e32 v166, 63, v0
	v_cmp_le_i32_e32 vcc, v167, v200
	s_nop 1
	v_cndmask_b32_e32 v66, v190, v66, vcc
	v_cmp_lt_i32_e32 vcc, v166, v200
	s_nop 1
	v_cndmask_b32_e32 v83, v190, v83, vcc
	v_cmp_le_i32_e32 vcc, v166, v200
	v_subrev_u32_e32 v166, 30, v0
	s_nop 0
	v_cndmask_b32_e32 v82, v190, v82, vcc
	v_cmp_le_i32_e32 vcc, v166, v200
	v_subrev_u32_e32 v166, 61, v0
	s_nop 0
	v_cndmask_b32_e32 v67, v190, v67, vcc
	v_cmp_le_i32_e32 vcc, v166, v200
	v_subrev_u32_e32 v166, 29, v0
	s_nop 0
	v_cndmask_b32_e32 v84, v190, v84, vcc
	v_cmp_le_i32_e32 vcc, v166, v200
	v_subrev_u32_e32 v166, 60, v0
	s_nop 0
	v_cndmask_b32_e32 v68, v190, v68, vcc
	v_cmp_le_i32_e32 vcc, v166, v200
	v_subrev_u32_e32 v166, 28, v0
	s_nop 0
	v_cndmask_b32_e32 v85, v190, v85, vcc
	v_cmp_le_i32_e32 vcc, v166, v200
	v_subrev_u32_e32 v166, 55, v0
	s_nop 0
	v_cndmask_b32_e32 v69, v190, v69, vcc
	v_cmp_le_i32_e32 vcc, v166, v200
	v_subrev_u32_e32 v166, 23, v0
	s_nop 0
	v_cndmask_b32_e32 v86, v190, v86, vcc
	v_cmp_le_i32_e32 vcc, v166, v200
	v_subrev_u32_e32 v166, 54, v0
	s_nop 0
	v_cndmask_b32_e32 v70, v190, v70, vcc
	v_cmp_le_i32_e32 vcc, v166, v200
	v_subrev_u32_e32 v166, 22, v0
	s_nop 0
	v_cndmask_b32_e32 v87, v190, v87, vcc
	v_cmp_le_i32_e32 vcc, v166, v200
	v_subrev_u32_e32 v166, 53, v0
	s_nop 0
	v_cndmask_b32_e32 v71, v190, v71, vcc
	v_cmp_le_i32_e32 vcc, v166, v200
	v_subrev_u32_e32 v166, 21, v0
	s_nop 0
	v_cndmask_b32_e32 v88, v190, v88, vcc
	v_cmp_le_i32_e32 vcc, v166, v200
	v_subrev_u32_e32 v166, 52, v0
	s_nop 0
	v_cndmask_b32_e32 v72, v190, v72, vcc
	v_cmp_le_i32_e32 vcc, v166, v200
	v_subrev_u32_e32 v166, 20, v0
	s_nop 0
	v_cndmask_b32_e32 v89, v190, v89, vcc
	v_cmp_le_i32_e32 vcc, v166, v200
	v_subrev_u32_e32 v166, 47, v0
	s_nop 0
	v_cndmask_b32_e32 v73, v190, v73, vcc
	v_cmp_le_i32_e32 vcc, v166, v200
	v_add_u32_e32 v166, -15, v0
	s_nop 0
	v_cndmask_b32_e32 v90, v190, v90, vcc
	v_cmp_le_i32_e32 vcc, v166, v200
	v_subrev_u32_e32 v166, 46, v0
	s_nop 0
	v_cndmask_b32_e32 v74, v190, v74, vcc
	v_cmp_le_i32_e32 vcc, v166, v200
	v_add_u32_e32 v166, -14, v0
	s_nop 0
	v_cndmask_b32_e32 v91, v190, v91, vcc
	v_cmp_le_i32_e32 vcc, v166, v200
	v_subrev_u32_e32 v166, 45, v0
	s_nop 0
	v_cndmask_b32_e32 v75, v190, v75, vcc
	v_cmp_le_i32_e32 vcc, v166, v200
	v_add_u32_e32 v166, -13, v0
	s_nop 0
	v_cndmask_b32_e32 v92, v190, v92, vcc
	v_cmp_le_i32_e32 vcc, v166, v200
	v_subrev_u32_e32 v166, 44, v0
	s_nop 0
	v_cndmask_b32_e32 v76, v190, v76, vcc
	v_cmp_le_i32_e32 vcc, v166, v200
	v_add_u32_e32 v166, -12, v0
	s_nop 0
	v_cndmask_b32_e32 v93, v190, v93, vcc
	v_cmp_le_i32_e32 vcc, v166, v200
	v_subrev_u32_e32 v166, 39, v0
	s_nop 0
	v_cndmask_b32_e32 v77, v190, v77, vcc
	v_cmp_le_i32_e32 vcc, v166, v200
	v_add_u32_e32 v166, -7, v0
	s_nop 0
	v_cndmask_b32_e32 v94, v190, v94, vcc
	v_cmp_le_i32_e32 vcc, v166, v200
	v_subrev_u32_e32 v166, 38, v0
	s_nop 0
	v_cndmask_b32_e32 v78, v190, v78, vcc
	v_cmp_le_i32_e32 vcc, v166, v200
	v_add_u32_e32 v166, -6, v0
	s_nop 0
	v_cndmask_b32_e32 v95, v190, v95, vcc
	v_cmp_le_i32_e32 vcc, v166, v200
	v_subrev_u32_e32 v166, 37, v0
	s_nop 0
	v_cndmask_b32_e32 v79, v190, v79, vcc
	v_cmp_le_i32_e32 vcc, v166, v200
	v_add_u32_e32 v166, -5, v0
	s_nop 0
	v_cndmask_b32_e32 v96, v190, v96, vcc
	v_cmp_le_i32_e32 vcc, v166, v200
	v_subrev_u32_e32 v166, 36, v0
	v_add_u32_e32 v0, -4, v0
	v_cndmask_b32_e32 v80, v190, v80, vcc
	v_cmp_le_i32_e32 vcc, v166, v200
	s_nop 1
	v_cndmask_b32_e32 v97, v190, v97, vcc
	v_cmp_le_i32_e32 vcc, v0, v200
	s_nop 1
	v_cndmask_b32_e32 v81, v190, v81, vcc

; #define ATT_SBAR() __builtin_amdgcn_sched_barrier(0)
; #define PV_RD(D0, X) do { X[0] = PV_TRB(v_rd_off(D0, 0, 0)); X[1] = PV_TRB(v_rd_off(D0, 0, 1)); X[2] = PV_TRB(v_rd_off(D0, 1, 0)); X[3] = PV_TRB(v_rd_off(D0, 1, 1)); \
;                           X[4] = PV_TRB(v_rd_off(D0, 2, 0)); X[5] = PV_TRB(v_rd_off(D0, 2, 1)); X[6] = PV_TRB(v_rd_off(D0, 3, 0)); X[7] = PV_TRB(v_rd_off(D0, 3, 1)); } while (0)
; __device__ __forceinline__ void pv_d0(f32x16* o, int vb, bf16x8 pa0, bf16x8 pa1, bf16x8 pa2, bf16x8 pa3) {
;     ...
;     s16x4 F[8], G[8];
;     PV_RD(0, F); ATT_SBAR();
;     PV_RD(1, G); ATT_SBAR(); PV_MM(0, F); ATT_SBAR();
;     PV_RD(2, F); ATT_SBAR(); PV_MM(1, G); ATT_SBAR();
;     PV_RD(3, G); ATT_SBAR(); PV_MM(2, F); ATT_SBAR();
;     PV_MM(3, G);
;     ...
; }
.LBB0_849:
	ds_read_b64_tr_b16 v[66:67], v197 offset:16384
	ds_read_b64_tr_b16 v[68:69], v197 offset:18432
	ds_read_b64_tr_b16 v[70:71], v197 offset:20480
	ds_read_b64_tr_b16 v[72:73], v197 offset:22528
	ds_read_b64_tr_b16 v[74:75], v197 offset:24576
	ds_read_b64_tr_b16 v[76:77], v197 offset:26624
	ds_read_b64_tr_b16 v[78:79], v197 offset:28672
	ds_read_b64_tr_b16 v[80:81], v197 offset:30720
	ds_read_b64_tr_b16 v[82:83], v197 offset:16896
	ds_read_b64_tr_b16 v[84:85], v197 offset:18944
	ds_read_b64_tr_b16 v[86:87], v197 offset:20992
	ds_read_b64_tr_b16 v[88:89], v197 offset:23040
	ds_read_b64_tr_b16 v[90:91], v197 offset:25088
	ds_read_b64_tr_b16 v[92:93], v197 offset:27136
	ds_read_b64_tr_b16 v[94:95], v197 offset:29184
	ds_read_b64_tr_b16 v[96:97], v197 offset:31232
	s_waitcnt lgkmcnt(14)
	v_mfma_f32_32x32x16_bf16 v[18:33], v[166:169], v[66:69], v[18:33]
	s_waitcnt lgkmcnt(12)
	v_mfma_f32_32x32x16_bf16 v[18:33], v[170:173], v[70:73], v[18:33]
	s_waitcnt lgkmcnt(10)
	v_mfma_f32_32x32x16_bf16 v[18:33], v[174:177], v[74:77], v[18:33]
	s_waitcnt lgkmcnt(8)
	v_mfma_f32_32x32x16_bf16 v[18:33], v[178:181], v[78:81], v[18:33]
	ds_read_b64_tr_b16 v[66:67], v197 offset:17408
	ds_read_b64_tr_b16 v[68:69], v197 offset:19456
	ds_read_b64_tr_b16 v[70:71], v197 offset:21504
	ds_read_b64_tr_b16 v[72:73], v197 offset:23552
	ds_read_b64_tr_b16 v[74:75], v197 offset:25600
	ds_read_b64_tr_b16 v[76:77], v197 offset:27648
	ds_read_b64_tr_b16 v[78:79], v197 offset:29696
	ds_read_b64_tr_b16 v[80:81], v197 offset:31744
	s_waitcnt lgkmcnt(14)
	v_mfma_f32_32x32x16_bf16 v[34:49], v[166:169], v[82:85], v[34:49]
	s_waitcnt lgkmcnt(12)
	v_mfma_f32_32x32x16_bf16 v[34:49], v[170:173], v[86:89], v[34:49]
	s_waitcnt lgkmcnt(10)
	v_mfma_f32_32x32x16_bf16 v[34:49], v[174:177], v[90:93], v[34:49]
	s_waitcnt lgkmcnt(8)
	v_mfma_f32_32x32x16_bf16 v[34:49], v[178:181], v[94:97], v[34:49]
	ds_read_b64_tr_b16 v[82:83], v197 offset:17920
	ds_read_b64_tr_b16 v[84:85], v197 offset:19968
	ds_read_b64_tr_b16 v[86:87], v197 offset:22016
	ds_read_b64_tr_b16 v[88:89], v197 offset:24064
	ds_read_b64_tr_b16 v[90:91], v197 offset:26112
	ds_read_b64_tr_b16 v[92:93], v197 offset:28160
	ds_read_b64_tr_b16 v[94:95], v197 offset:30208
	ds_read_b64_tr_b16 v[96:97], v197 offset:32256
	s_waitcnt lgkmcnt(14)
	v_mfma_f32_32x32x16_bf16 v[50:65], v[166:169], v[66:69], v[50:65]
	s_waitcnt lgkmcnt(12)
	v_mfma_f32_32x32x16_bf16 v[50:65], v[170:173], v[70:73], v[50:65]
	s_waitcnt lgkmcnt(10)
	v_mfma_f32_32x32x16_bf16 v[50:65], v[174:177], v[74:77], v[50:65]
	s_waitcnt lgkmcnt(8)
	v_mfma_f32_32x32x16_bf16 v[50:65], v[178:181], v[78:81], v[50:65]
	s_waitcnt lgkmcnt(6)
	v_mfma_f32_32x32x16_bf16 v[2:17], v[166:169], v[82:85], v[2:17]
	s_waitcnt lgkmcnt(4)
	v_mfma_f32_32x32x16_bf16 v[2:17], v[170:173], v[86:89], v[2:17]
	s_waitcnt lgkmcnt(2)
	v_mfma_f32_32x32x16_bf16 v[2:17], v[174:177], v[90:93], v[2:17]
	s_waitcnt lgkmcnt(0)
	v_mfma_f32_32x32x16_bf16 v[2:17], v[178:181], v[94:97], v[2:17]
	s_waitcnt lgkmcnt(0)
	s_barrier
	s_waitcnt vmcnt(0)
	s_cmp_lt_i32 s11, -1
	s_cbranch_scc0 .LBB0_851
	v_add_u32_e32 v0, s82, v188
	s_waitcnt vmcnt(2)
	ds_write_b128 v0, v[146:149] offset:32768
	s_waitcnt vmcnt(1)
	ds_write_b128 v0, v[150:153] offset:45568
	v_add_u32_e32 v0, s82, v186
	s_waitcnt vmcnt(0)
	ds_write_b128 v0, v[154:157] offset:33024
